# v39 plus three small timing-only edits: setprio pair removal, barrier leader publish-before-invalidate, P4b b_i load hoisted
# baseline (speedup 1.0000x reference)
.LBB0_93:
	s_or_b64 exec, exec, s[6:7]
	buffer_inv sc1
	s_waitcnt vmcnt(0)

.LBB0_150:
	s_or_b64 exec, exec, s[2:3]
	s_mov_b64 s[2:3], exec
	v_mbcnt_lo_u32_b32 v0, s2, 0
	v_mbcnt_hi_u32_b32 v0, s3, v0
	v_cmp_eq_u32_e32 vcc, 0, v0
	s_waitcnt vmcnt(0)
	s_and_saveexec_b64 s[6:7], vcc
	s_cbranch_execz .LBB0_152
	s_bcnt1_i32_b64 s2, s[2:3]
	v_mov_b32_e32 v0, s2
	global_atomic_add v219, v0, s[4:5] offset:1024

.LBB0_870:
	v_readlane_b32 s13, v254, 45
	s_or_b32 s12, s12, s13
	s_ashr_i32 s13, s12, 31
	v_readlane_b32 s14, v254, 11
	s_xor_b64 s[10:11], s[2:3], -1
	s_lshl_b64 s[14:15], s[12:13], s14
	s_add_u32 s14, s14, s5
	v_readlane_b32 s16, v254, 25
	s_addc_u32 s15, s15, 0
	s_lshl_b64 s[12:13], s[12:13], s16
	s_add_u32 s12, s12, s4
	s_addc_u32 s13, s13, 0
	s_and_b64 s[16:17], s[2:3], exec
	s_cselect_b32 s16, 0, s33
	s_lshl_b64 s[68:69], s[12:13], 2
	v_readlane_b32 s17, v254, 51
	s_add_u32 s68, s17, s68
	v_readlane_b32 s17, v254, 52
	s_addc_u32 s69, s17, s69
	s_lshl_b64 s[14:15], s[14:15], 2
	v_lshl_add_u64 v[0:1], v[148:149], 0, s[14:15]
	v_lshl_add_u32 v15, s16, 13, v215
	global_load_dword v228, v175, s[68:69]
	global_load_dword v8, v[0:1], off
	v_lshl_add_u64 v[58:59], v[150:151], 0, s[14:15]
	global_load_dword v229, v[58:59], off
	ds_read_b128 v[0:3], v15 offset:32768
	ds_read_b128 v[4:7], v15 offset:33792
	s_waitcnt lgkmcnt(0)
	v_mfma_f32_32x32x16_bf16 v[32:47], v[0:3], v[80:83], 0
	ds_read_b128 v[0:3], v15 offset:34816
	v_readlane_b32 s68, v254, 43
	v_readlane_b32 s69, v254, 44
	s_and_b64 s[74:75], s[2:3], exec
	v_cndmask_b32_e64 v18, 0, 1, s[20:21]
	v_cndmask_b32_e64 v9, 0, 1, s[68:69]
	v_readlane_b32 s68, v254, 39
	v_mfma_f32_32x32x16_bf16 v[32:47], v[4:7], v[84:87], v[32:47]
	ds_read_b128 v[4:7], v15 offset:35840
	v_readlane_b32 s69, v254, 40
	v_cndmask_b32_e64 v20, 0, 1, s[24:25]
	v_cndmask_b32_e64 v21, 0, 1, s[22:23]
	v_cndmask_b32_e64 v10, 0, 1, s[68:69]
	v_readlane_b32 s68, v252, 7
	v_readlane_b32 s69, v252, 8
	s_waitcnt lgkmcnt(0)
	v_mfma_f32_32x32x16_bf16 v[32:47], v[0:3], v[88:91], v[32:47]
	ds_read_b128 v[0:3], v15 offset:36864
	v_cndmask_b32_e64 v11, 0, 1, s[68:69]
	v_readlane_b32 s68, v254, 41
	v_readlane_b32 s69, v254, 42
	v_cndmask_b32_e64 v22, 0, 1, s[18:19]
	v_cndmask_b32_e64 v23, 0, 1, s[26:27]
	v_cndmask_b32_e64 v12, 0, 1, s[68:69]
	v_mfma_f32_32x32x16_bf16 v[32:47], v[4:7], v[92:95], v[32:47]
	ds_read_b128 v[4:7], v15 offset:37888
	v_readlane_b32 s68, v252, 11
	v_readlane_b32 s69, v252, 12
	v_cndmask_b32_e64 v24, 0, 1, s[34:35]
	v_cndmask_b32_e64 v25, 0, 1, s[30:31]
	v_cndmask_b32_e64 v13, 0, 1, s[68:69]
	v_readlane_b32 s68, v252, 9
	s_waitcnt lgkmcnt(0)
	v_mfma_f32_32x32x16_bf16 v[32:47], v[0:3], v[96:99], v[32:47]
	ds_read_b128 v[0:3], v15 offset:38912
	v_readlane_b32 s69, v252, 10
	v_cndmask_b32_e64 v26, 0, 1, s[38:39]
	v_cndmask_b32_e64 v27, 0, 1, s[36:37]
	v_cndmask_b32_e64 v14, 0, 1, s[68:69]
	v_readlane_b32 s68, v252, 15
	v_readlane_b32 s69, v252, 16
	v_mfma_f32_32x32x16_bf16 v[32:47], v[4:7], v[100:103], v[32:47]
	ds_read_b128 v[4:7], v15 offset:39936
	v_cndmask_b32_e64 v16, 0, 1, s[68:69]
	v_readlane_b32 s68, v252, 13
	v_readlane_b32 s69, v252, 14
	v_cndmask_b32_e64 v28, 0, 1, s[42:43]
	v_cndmask_b32_e64 v29, 0, 1, s[40:41]
	v_cndmask_b32_e64 v17, 0, 1, s[68:69]
	s_waitcnt lgkmcnt(0)
	v_mfma_f32_32x32x16_bf16 v[32:47], v[0:3], v[104:107], v[32:47]
	v_readlane_b32 s68, v252, 17
	v_readlane_b32 s69, v252, 18
	v_cndmask_b32_e64 v30, 0, 1, s[46:47]
	v_cndmask_b32_e64 v31, 0, 1, s[44:45]
	v_cndmask_b32_e64 v19, 0, 1, s[68:69]
	v_cndmask_b32_e64 v48, 0, 1, s[50:51]
	v_cndmask_b32_e64 v49, 0, 1, s[48:49]
	v_cndmask_b32_e64 v50, 0, 1, s[54:55]
	v_cndmask_b32_e64 v51, 0, 1, s[52:53]
	v_cndmask_b32_e64 v52, 0, 1, s[58:59]
	v_cndmask_b32_e64 v53, 0, 1, s[56:57]
	v_cndmask_b32_e64 v54, 0, 1, s[62:63]
	v_cndmask_b32_e64 v55, 0, 1, s[60:61]
	s_cselect_b32 s17, s33, 3
	v_mfma_f32_32x32x16_bf16 v[32:47], v[4:7], v[108:111], v[32:47]
	s_lshl_b32 s78, s16, 10
	v_cndmask_b32_e64 v9, v10, v9, s[2:3]
	v_cndmask_b32_e64 v10, v12, v11, s[2:3]
	s_waitcnt vmcnt(0)
	v_max_f32_e32 v0, v228, v228
	v_max_f32_e32 v1, v8, v8
	v_max_f32_e32 v230, v0, v1
	v_cndmask_b32_e64 v0, 0, 1, s[66:67]
	v_cndmask_b32_e64 v1, 0, 1, s[64:65]
	v_cndmask_b32_e64 v11, v14, v13, s[2:3]
	v_cndmask_b32_e64 v12, v17, v16, s[2:3]
	v_cndmask_b32_e64 v13, v19, v18, s[2:3]
	v_cndmask_b32_e64 v14, v21, v20, s[2:3]
	v_cndmask_b32_e64 v16, v23, v22, s[2:3]
	v_cndmask_b32_e64 v17, v25, v24, s[2:3]
	v_cndmask_b32_e64 v18, v27, v26, s[2:3]
	v_cndmask_b32_e64 v19, v29, v28, s[2:3]
	v_cndmask_b32_e64 v20, v31, v30, s[2:3]
	v_cndmask_b32_e64 v21, v49, v48, s[2:3]
	v_cndmask_b32_e64 v22, v51, v50, s[2:3]
	v_cndmask_b32_e64 v23, v53, v52, s[2:3]
	v_cndmask_b32_e64 v24, v55, v54, s[2:3]
	v_cndmask_b32_e64 v0, v1, v0, s[2:3]
	s_add_u32 s2, s14, 0x23b00040
	v_add_lshl_u32 v174, v217, s78, 1
	v_lshlrev_b32_e32 v209, 2, v214
	s_addc_u32 s3, s15, 0
	v_lshl_add_u64 v[156:157], s[6:7], 0, v[174:175]
	v_lshl_or_b32 v174, s16, 7, v209
	v_lshl_add_u64 v[158:159], s[2:3], 0, v[174:175]
	v_add_lshl_u32 v174, v218, s78, 1
	v_lshl_add_u64 v[160:161], s[6:7], 0, v[174:175]
	v_add_lshl_u32 v174, v220, s78, 1
	v_or_b32_e32 v2, s78, v216
	v_and_b32_e32 v1, 1, v13
	v_lshl_add_u64 v[162:163], s[6:7], 0, v[174:175]
	v_lshlrev_b32_e32 v174, 1, v2
	v_and_b32_e32 v9, 1, v9
	v_and_b32_e32 v10, 1, v10
	v_and_b32_e32 v11, 1, v11
	v_and_b32_e32 v12, 1, v12
	v_cmp_eq_u32_e64 s[76:77], 1, v1
	v_and_b32_e32 v1, 1, v14
	v_lshl_add_u64 v[164:165], s[8:9], 0, v[174:175]
	v_add_lshl_u32 v174, v221, s78, 1
	v_and_b32_e32 v48, 1, v16
	v_and_b32_e32 v49, 1, v17
	v_and_b32_e32 v50, 1, v18
	v_and_b32_e32 v51, 1, v19
	v_and_b32_e32 v52, 1, v20
	v_and_b32_e32 v53, 1, v21
	v_and_b32_e32 v54, 1, v22
	v_and_b32_e32 v55, 1, v23
	v_and_b32_e32 v56, 1, v24
	v_and_b32_e32 v57, 1, v0
	v_cmp_eq_u32_e64 s[68:69], 1, v9
	v_cmp_eq_u32_e64 s[70:71], 1, v10
	v_cmp_eq_u32_e64 s[72:73], 1, v11
	v_mul_f32_e32 v231, 0x3fb8aa3b, v230
	v_cmp_eq_u32_e64 s[74:75], 1, v12
	v_cmp_eq_u32_e64 s[78:79], 1, v1
	v_lshl_add_u64 v[166:167], s[6:7], 0, v[174:175]
	v_mov_b32_e32 v174, 0
	v_mov_b32_e32 v0, 0
	v_mov_b32_e32 v1, v227
	v_mov_b32_e32 v2, v227
	v_mov_b32_e32 v3, v227
	v_mov_b32_e32 v4, v227
	v_mov_b32_e32 v5, v227
	v_mov_b32_e32 v6, v227
	v_mov_b32_e32 v7, v227
	v_mov_b32_e32 v8, v227
	v_mov_b32_e32 v9, v227
	v_mov_b32_e32 v10, v227
	v_mov_b32_e32 v11, v227
	v_mov_b32_e32 v12, v227
	v_mov_b32_e32 v13, v227
	v_mov_b32_e32 v14, v227
	v_mov_b32_e32 v15, v227
	v_mov_b32_e32 v16, 0
	v_mov_b32_e32 v17, v227
	v_mov_b32_e32 v18, v227
	v_mov_b32_e32 v19, v227
	v_mov_b32_e32 v20, v227
	v_mov_b32_e32 v21, v227
	v_mov_b32_e32 v22, v227
	v_mov_b32_e32 v23, v227
	v_mov_b32_e32 v24, v227
	v_mov_b32_e32 v25, v227
	v_mov_b32_e32 v26, v227
	v_mov_b32_e32 v27, v227
	v_mov_b32_e32 v28, v227
	v_mov_b32_e32 v29, v227
	v_mov_b32_e32 v30, v227
	v_mov_b32_e32 v31, v227
	v_cmp_eq_u32_e64 s[80:81], 1, v48
	v_cmp_eq_u32_e64 s[82:83], 1, v49
	v_cmp_eq_u32_e64 s[84:85], 1, v50
	v_cmp_eq_u32_e64 s[86:87], 1, v51
	v_cmp_eq_u32_e64 s[88:89], 1, v52
	v_cmp_eq_u32_e64 s[90:91], 1, v53
	v_cmp_eq_u32_e64 s[92:93], 1, v54
	v_cmp_eq_u32_e64 s[94:95], 1, v55
	v_cmp_eq_u32_e64 s[96:97], 1, v56
	v_cmp_eq_u32_e64 s[2:3], 1, v57

.LBB0_1020:
	s_or_b64 exec, exec, s[6:7]
	s_mov_b64 s[6:7], exec
	v_mbcnt_lo_u32_b32 v0, s6, 0
	v_mbcnt_hi_u32_b32 v0, s7, v0
	v_cmp_eq_u32_e32 vcc, 0, v0
	s_waitcnt vmcnt(0)
	s_and_saveexec_b64 s[10:11], vcc
	s_cbranch_execz .LBB0_1022
	s_bcnt1_i32_b64 s6, s[6:7]
	v_mov_b32_e32 v0, s6
	global_atomic_add v219, v0, s[8:9] offset:1024
.LBB0_1022:
	s_or_b64 exec, exec, s[10:11]
	buffer_inv sc1
	s_waitcnt vmcnt(0)

.LBB0_1189:
	s_or_b64 exec, exec, s[2:3]
	s_mov_b64 s[2:3], exec
	v_mbcnt_lo_u32_b32 v0, s2, 0
	v_mbcnt_hi_u32_b32 v0, s3, v0
	v_cmp_eq_u32_e32 vcc, 0, v0
	s_waitcnt vmcnt(0)
	s_and_saveexec_b64 s[6:7], vcc
	s_cbranch_execz .LBB0_93
	s_bcnt1_i32_b64 s2, s[2:3]
	v_mov_b32_e32 v0, s2
	global_atomic_add v219, v0, s[4:5] offset:1024
	s_branch .LBB0_93
